# last layer MLP2 epilogue: bf16 residual copy and row sum-of-squares partials (no consumer after the final layer) are not written
# speedup vs baseline: 1.0193x; 1.0042x over previous
.LBB0_1696:
	v_readlane_b32 s40, v251, 47
	s_nop 0
	s_cmp_eq_u32 s40, 3
	s_cbranch_scc1 .Lres_mlp2_last
	v_readfirstlane_b32 s40, v204
	s_lshr_b32 s40, s40, 6
	s_and_b32 s41, s40, 1
	s_bfe_u32 s42, s40, 0x10001
	s_lshr_b32 s43, s40, 2
	s_lshl_b32 s44, s4, 1
	s_add_i32 s44, s44, s42
	s_lshl_b32 s45, s44, 7
	s_lshl_b32 s46, s41, 6
	s_add_i32 s45, s45, s46
	s_lshl_b32 s46, s43, 7
	s_add_i32 s46, s46, s2
	s_lshl_b32 s47, s44, 1
	s_add_i32 s47, s47, s41
	v_readlane_b32 s36, v250, 9
	v_readlane_b32 s37, v250, 10
	s_mov_b64 s[38:39], s[36:37]
	v_readlane_b32 s50, v250, 11
	v_readlane_b32 s51, v250, 12
	s_add_u32 s34, s50, 0xf900000
	s_addc_u32 s35, s51, 0
	s_add_u32 s50, s50, 0x5800000
	s_addc_u32 s51, s51, 0
	s_lshl_b32 s48, s46, 12
	s_lshl_b32 s49, s45, 2
	s_add_u32 s48, s48, s49
	s_add_u32 s36, s36, s48
	s_addc_u32 s37, s37, 0
	s_add_u32 s38, s38, s48
	s_addc_u32 s39, s39, 0
	s_lshr_b32 s48, s48, 1
	s_add_u32 s50, s50, s48
	s_addc_u32 s51, s51, 0
	s_lshl_b32 s48, s46, 6
	s_lshl_b32 s49, s47, 2
	s_add_u32 s48, s48, s49
	s_add_u32 s34, s34, s48
	s_addc_u32 s35, s35, 0
	v_and_b32_e32 v249, 63, v204
	v_and_b32_e32 v170, 31, v249
	v_lshrrev_b32_e32 v171, 5, v249
	v_and_b32_e32 v208, 15, v249
	v_lshrrev_b32_e32 v209, 4, v249
	s_lshl_b32 s40, s40, 14
	v_and_b32_e32 v238, 15, v170
	v_xor_b32_e32 v238, v238, v171
	v_lshl_add_u32 v239, v170, 8, s40
	v_xor_b32_e32 v228, 0, v238
	v_lshl_add_u32 v228, v228, 4, v239
	v_xor_b32_e32 v229, 2, v238
	v_lshl_add_u32 v229, v229, 4, v239
	v_xor_b32_e32 v230, 4, v238
	v_lshl_add_u32 v230, v230, 4, v239
	v_xor_b32_e32 v231, 6, v238
	v_lshl_add_u32 v231, v231, 4, v239
	v_xor_b32_e32 v232, 8, v238
	v_lshl_add_u32 v232, v232, 4, v239
	v_xor_b32_e32 v233, 10, v238
	v_lshl_add_u32 v233, v233, 4, v239
	v_xor_b32_e32 v234, 12, v238
	v_lshl_add_u32 v234, v234, 4, v239
	v_xor_b32_e32 v235, 14, v238
	v_lshl_add_u32 v235, v235, 4, v239
	v_lshl_add_u32 v239, v209, 8, s40
	v_add_u32_e32 v210, 0, v209
	v_xor_b32_e32 v210, v210, v208
	v_lshl_add_u32 v210, v210, 4, v239
	v_add_u32_e32 v211, 4, v209
	v_xor_b32_e32 v211, v211, v208
	v_lshl_add_u32 v211, v211, 4, v239
	v_add_u32_e32 v215, 8, v209
	v_xor_b32_e32 v215, v215, v208
	v_lshl_add_u32 v215, v215, 4, v239
	v_add_u32_e32 v237, 12, v209
	v_xor_b32_e32 v237, v237, v208
	v_lshl_add_u32 v237, v237, 4, v239
	v_lshlrev_b32_e32 v247, 12, v209
	v_lshl_add_u32 v247, v208, 4, v247
	v_lshrrev_b32_e32 v248, 1, v247
	v_lshlrev_b32_e32 v249, 6, v209
	s_mov_b32 s48, 0x00010001
	s_mov_b32 s49, 0x00010001
	global_load_dwordx4 v[130:133], v247, s[36:37]
	s_add_u32 s36, s36, 0x4000
	s_addc_u32 s37, s37, 0
	global_load_dwordx4 v[134:137], v247, s[36:37]
	s_add_u32 s36, s36, 0x4000
	s_addc_u32 s37, s37, 0
	global_load_dwordx4 v[138:141], v247, s[36:37]
	s_add_u32 s36, s36, 0x4000
	s_addc_u32 s37, s37, 0
	global_load_dwordx4 v[142:145], v247, s[36:37]
	s_add_u32 s36, s36, 0x4000
	s_addc_u32 s37, s37, 0
	global_load_dwordx4 v[146:149], v247, s[36:37]
	s_add_u32 s36, s36, 0x4000
	s_addc_u32 s37, s37, 0
	global_load_dwordx4 v[150:153], v247, s[36:37]
	s_add_u32 s36, s36, 0x4000
	s_addc_u32 s37, s37, 0
	global_load_dwordx4 v[154:157], v247, s[36:37]
	s_add_u32 s36, s36, 0x4000
	s_addc_u32 s37, s37, 0
	global_load_dwordx4 v[158:161], v247, s[36:37]
	s_add_u32 s36, s36, 0x4000
	s_addc_u32 s37, s37, 0
	global_load_dwordx4 v[162:165], v247, s[36:37]
	s_add_u32 s36, s36, 0x4000
	s_addc_u32 s37, s37, 0
	global_load_dwordx4 v[166:169], v247, s[36:37]
	s_add_u32 s36, s36, 0x4000
	s_addc_u32 s37, s37, 0
	global_load_dwordx4 v[192:195], v247, s[36:37]
	s_add_u32 s36, s36, 0x4000
	s_addc_u32 s37, s37, 0
	global_load_dwordx4 v[196:199], v247, s[36:37]
	s_add_u32 s36, s36, 0x4000
	s_addc_u32 s37, s37, 0
	global_load_dwordx4 v[200:203], v247, s[36:37]
	s_add_u32 s36, s36, 0x4000
	s_addc_u32 s37, s37, 0
	global_load_dwordx4 v[216:219], v247, s[36:37]
	s_add_u32 s36, s36, 0x4000
	s_addc_u32 s37, s37, 0
	global_load_dwordx4 v[220:223], v247, s[36:37]
	s_add_u32 s36, s36, 0x4000
	s_addc_u32 s37, s37, 0
	global_load_dwordx4 v[224:227], v247, s[36:37]
	s_add_u32 s36, s36, 0x4000
	s_addc_u32 s37, s37, 0
	ds_write_b128 v228, v[66:69]
	ds_write_b128 v229, v[70:73]
	ds_write_b128 v230, v[74:77]
	ds_write_b128 v231, v[78:81]
	ds_write_b128 v232, v[114:117]
	ds_write_b128 v233, v[118:121]
	ds_write_b128 v234, v[122:125]
	ds_write_b128 v235, v[126:129]
	ds_write_b128 v228, v[82:85] offset:8192
	ds_write_b128 v229, v[86:89] offset:8192
	ds_write_b128 v230, v[90:93] offset:8192
	ds_write_b128 v231, v[94:97] offset:8192
	ds_write_b128 v232, v[98:101] offset:8192
	ds_write_b128 v233, v[102:105] offset:8192
	ds_write_b128 v234, v[106:109] offset:8192
	ds_write_b128 v235, v[110:113] offset:8192
	global_load_dwordx4 v[66:69], v247, s[36:37]
	s_add_u32 s36, s36, 0x4000
	s_addc_u32 s37, s37, 0
	global_load_dwordx4 v[70:73], v247, s[36:37]
	s_add_u32 s36, s36, 0x4000
	s_addc_u32 s37, s37, 0
	global_load_dwordx4 v[74:77], v247, s[36:37]
	s_add_u32 s36, s36, 0x4000
	s_addc_u32 s37, s37, 0
	global_load_dwordx4 v[78:81], v247, s[36:37]
	s_add_u32 s36, s36, 0x4000
	s_addc_u32 s37, s37, 0
	global_load_dwordx4 v[114:117], v247, s[36:37]
	s_add_u32 s36, s36, 0x4000
	s_addc_u32 s37, s37, 0
	global_load_dwordx4 v[118:121], v247, s[36:37]
	s_add_u32 s36, s36, 0x4000
	s_addc_u32 s37, s37, 0
	global_load_dwordx4 v[122:125], v247, s[36:37]
	s_add_u32 s36, s36, 0x4000
	s_addc_u32 s37, s37, 0
	global_load_dwordx4 v[126:129], v247, s[36:37]
	s_add_u32 s36, s36, 0x4000
	s_addc_u32 s37, s37, 0
	global_load_dwordx4 v[82:85], v247, s[36:37]
	s_add_u32 s36, s36, 0x4000
	s_addc_u32 s37, s37, 0
	global_load_dwordx4 v[86:89], v247, s[36:37]
	s_add_u32 s36, s36, 0x4000
	s_addc_u32 s37, s37, 0
	global_load_dwordx4 v[90:93], v247, s[36:37]
	s_add_u32 s36, s36, 0x4000
	s_addc_u32 s37, s37, 0
	global_load_dwordx4 v[94:97], v247, s[36:37]
	s_add_u32 s36, s36, 0x4000
	s_addc_u32 s37, s37, 0
	global_load_dwordx4 v[98:101], v247, s[36:37]
	s_add_u32 s36, s36, 0x4000
	s_addc_u32 s37, s37, 0
	global_load_dwordx4 v[102:105], v247, s[36:37]
	s_add_u32 s36, s36, 0x4000
	s_addc_u32 s37, s37, 0
	global_load_dwordx4 v[106:109], v247, s[36:37]
	s_add_u32 s36, s36, 0x4000
	s_addc_u32 s37, s37, 0
	global_load_dwordx4 v[110:113], v247, s[36:37]
	s_add_u32 s36, s36, 0x4000
	s_addc_u32 s37, s37, 0
	s_waitcnt lgkmcnt(0)
	ds_read_b128 v[228:231], v210 offset:0
	ds_read_b128 v[238:241], v211 offset:1024
	s_waitcnt vmcnt(31) lgkmcnt(1)
	v_pk_add_f32 v[130:131], v[228:229], v[130:131]
	v_pk_add_f32 v[132:133], v[230:231], v[132:133]
	v_pk_mul_f32 v[232:233], v[130:131], v[130:131]
	v_pk_mul_f32 v[234:235], v[132:133], v[132:133]
	ds_read_b128 v[228:231], v215 offset:2048
	v_add_f32_e32 v236, v232, v233
	v_add_f32_e32 v236, v234, v236
	v_add_f32_e32 v236, v235, v236
	global_store_dwordx4 v247, v[130:133], s[38:39]
	v_cvt_pk_bf16_f32 v232, v130, v131
	v_cvt_pk_bf16_f32 v233, v132, v133
	v_add_f32_dpp v236, v236, v236 quad_perm:[1,0,3,2] row_mask:0xf bank_mask:0xf
	global_store_dwordx2 v248, v[232:233], s[50:51]
	s_add_u32 s38, s38, 0x4000
	s_addc_u32 s39, s39, 0
	v_add_f32_dpp v236, v236, v236 quad_perm:[2,3,0,1] row_mask:0xf bank_mask:0xf
	s_add_u32 s50, s50, 0x2000
	s_addc_u32 s51, s51, 0
	v_add_f32_dpp v236, v236, v236 row_half_mirror row_mask:0xf bank_mask:0xf
	s_nop 1
	v_add_f32_dpp v236, v236, v236 row_mirror row_mask:0xf bank_mask:0xf
	s_mov_b64 exec, s[48:49]
	global_store_dword v249, v236, s[34:35] offset:0
	s_mov_b64 exec, -1
	s_waitcnt vmcnt(33) lgkmcnt(1)
	v_pk_add_f32 v[134:135], v[238:239], v[134:135]
	v_pk_add_f32 v[136:137], v[240:241], v[136:137]
	v_pk_mul_f32 v[242:243], v[134:135], v[134:135]
	v_pk_mul_f32 v[244:245], v[136:137], v[136:137]
	ds_read_b128 v[238:241], v237 offset:3072
	v_add_f32_e32 v246, v242, v243
	v_add_f32_e32 v246, v244, v246
	v_add_f32_e32 v246, v245, v246
	global_store_dwordx4 v247, v[134:137], s[38:39]
	v_cvt_pk_bf16_f32 v242, v134, v135
	v_cvt_pk_bf16_f32 v243, v136, v137
	v_add_f32_dpp v246, v246, v246 quad_perm:[1,0,3,2] row_mask:0xf bank_mask:0xf
	global_store_dwordx2 v248, v[242:243], s[50:51]
	s_add_u32 s38, s38, 0x4000
	s_addc_u32 s39, s39, 0
	v_add_f32_dpp v246, v246, v246 quad_perm:[2,3,0,1] row_mask:0xf bank_mask:0xf
	s_add_u32 s50, s50, 0x2000
	s_addc_u32 s51, s51, 0
	v_add_f32_dpp v246, v246, v246 row_half_mirror row_mask:0xf bank_mask:0xf
	s_nop 1
	v_add_f32_dpp v246, v246, v246 row_mirror row_mask:0xf bank_mask:0xf
	s_mov_b64 exec, s[48:49]
	global_store_dword v249, v246, s[34:35] offset:256
	s_mov_b64 exec, -1
	s_waitcnt vmcnt(35) lgkmcnt(1)
	v_pk_add_f32 v[138:139], v[228:229], v[138:139]
	v_pk_add_f32 v[140:141], v[230:231], v[140:141]
	v_pk_mul_f32 v[232:233], v[138:139], v[138:139]
	v_pk_mul_f32 v[234:235], v[140:141], v[140:141]
	ds_read_b128 v[228:231], v210 offset:4096
	v_add_f32_e32 v236, v232, v233
	v_add_f32_e32 v236, v234, v236
	v_add_f32_e32 v236, v235, v236
	global_store_dwordx4 v247, v[138:141], s[38:39]
	v_cvt_pk_bf16_f32 v232, v138, v139
	v_cvt_pk_bf16_f32 v233, v140, v141
	v_add_f32_dpp v236, v236, v236 quad_perm:[1,0,3,2] row_mask:0xf bank_mask:0xf
	global_store_dwordx2 v248, v[232:233], s[50:51]
	s_add_u32 s38, s38, 0x4000
	s_addc_u32 s39, s39, 0
	v_add_f32_dpp v236, v236, v236 quad_perm:[2,3,0,1] row_mask:0xf bank_mask:0xf
	s_add_u32 s50, s50, 0x2000
	s_addc_u32 s51, s51, 0
	v_add_f32_dpp v236, v236, v236 row_half_mirror row_mask:0xf bank_mask:0xf
	s_nop 1
	v_add_f32_dpp v236, v236, v236 row_mirror row_mask:0xf bank_mask:0xf
	s_mov_b64 exec, s[48:49]
	global_store_dword v249, v236, s[34:35] offset:512
	s_mov_b64 exec, -1
	s_waitcnt vmcnt(37) lgkmcnt(1)
	v_pk_add_f32 v[142:143], v[238:239], v[142:143]
	v_pk_add_f32 v[144:145], v[240:241], v[144:145]
	v_pk_mul_f32 v[242:243], v[142:143], v[142:143]
	v_pk_mul_f32 v[244:245], v[144:145], v[144:145]
	ds_read_b128 v[238:241], v211 offset:5120
	v_add_f32_e32 v246, v242, v243
	v_add_f32_e32 v246, v244, v246
	v_add_f32_e32 v246, v245, v246
	global_store_dwordx4 v247, v[142:145], s[38:39]
	v_cvt_pk_bf16_f32 v242, v142, v143
	v_cvt_pk_bf16_f32 v243, v144, v145
	v_add_f32_dpp v246, v246, v246 quad_perm:[1,0,3,2] row_mask:0xf bank_mask:0xf
	global_store_dwordx2 v248, v[242:243], s[50:51]
	s_add_u32 s38, s38, 0x4000
	s_addc_u32 s39, s39, 0
	v_add_f32_dpp v246, v246, v246 quad_perm:[2,3,0,1] row_mask:0xf bank_mask:0xf
	s_add_u32 s50, s50, 0x2000
	s_addc_u32 s51, s51, 0
	v_add_f32_dpp v246, v246, v246 row_half_mirror row_mask:0xf bank_mask:0xf
	s_nop 1
	v_add_f32_dpp v246, v246, v246 row_mirror row_mask:0xf bank_mask:0xf
	s_mov_b64 exec, s[48:49]
	global_store_dword v249, v246, s[34:35] offset:768
	s_mov_b64 exec, -1
	s_waitcnt vmcnt(39) lgkmcnt(1)
	v_pk_add_f32 v[146:147], v[228:229], v[146:147]
	v_pk_add_f32 v[148:149], v[230:231], v[148:149]
	v_pk_mul_f32 v[232:233], v[146:147], v[146:147]
	v_pk_mul_f32 v[234:235], v[148:149], v[148:149]
	ds_read_b128 v[228:231], v215 offset:6144
	v_add_f32_e32 v236, v232, v233
	v_add_f32_e32 v236, v234, v236
	v_add_f32_e32 v236, v235, v236
	global_store_dwordx4 v247, v[146:149], s[38:39]
	v_cvt_pk_bf16_f32 v232, v146, v147
	v_cvt_pk_bf16_f32 v233, v148, v149
	v_add_f32_dpp v236, v236, v236 quad_perm:[1,0,3,2] row_mask:0xf bank_mask:0xf
	global_store_dwordx2 v248, v[232:233], s[50:51]
	s_add_u32 s38, s38, 0x4000
	s_addc_u32 s39, s39, 0
	v_add_f32_dpp v236, v236, v236 quad_perm:[2,3,0,1] row_mask:0xf bank_mask:0xf
	s_add_u32 s50, s50, 0x2000
	s_addc_u32 s51, s51, 0
	v_add_f32_dpp v236, v236, v236 row_half_mirror row_mask:0xf bank_mask:0xf
	s_nop 1
	v_add_f32_dpp v236, v236, v236 row_mirror row_mask:0xf bank_mask:0xf
	s_mov_b64 exec, s[48:49]
	global_store_dword v249, v236, s[34:35] offset:1024
	s_mov_b64 exec, -1
	s_waitcnt vmcnt(41) lgkmcnt(1)
	v_pk_add_f32 v[150:151], v[238:239], v[150:151]
	v_pk_add_f32 v[152:153], v[240:241], v[152:153]
	v_pk_mul_f32 v[242:243], v[150:151], v[150:151]
	v_pk_mul_f32 v[244:245], v[152:153], v[152:153]
	ds_read_b128 v[238:241], v237 offset:7168
	v_add_f32_e32 v246, v242, v243
	v_add_f32_e32 v246, v244, v246
	v_add_f32_e32 v246, v245, v246
	global_store_dwordx4 v247, v[150:153], s[38:39]
	v_cvt_pk_bf16_f32 v242, v150, v151
	v_cvt_pk_bf16_f32 v243, v152, v153
	v_add_f32_dpp v246, v246, v246 quad_perm:[1,0,3,2] row_mask:0xf bank_mask:0xf
	global_store_dwordx2 v248, v[242:243], s[50:51]
	s_add_u32 s38, s38, 0x4000
	s_addc_u32 s39, s39, 0
	v_add_f32_dpp v246, v246, v246 quad_perm:[2,3,0,1] row_mask:0xf bank_mask:0xf
	s_add_u32 s50, s50, 0x2000
	s_addc_u32 s51, s51, 0
	v_add_f32_dpp v246, v246, v246 row_half_mirror row_mask:0xf bank_mask:0xf
	s_nop 1
	v_add_f32_dpp v246, v246, v246 row_mirror row_mask:0xf bank_mask:0xf
	s_mov_b64 exec, s[48:49]
	global_store_dword v249, v246, s[34:35] offset:1280
	s_mov_b64 exec, -1
	s_waitcnt vmcnt(43) lgkmcnt(1)
	v_pk_add_f32 v[154:155], v[228:229], v[154:155]
	v_pk_add_f32 v[156:157], v[230:231], v[156:157]
	v_pk_mul_f32 v[232:233], v[154:155], v[154:155]
	v_pk_mul_f32 v[234:235], v[156:157], v[156:157]
	ds_read_b128 v[228:231], v210 offset:8192
	v_add_f32_e32 v236, v232, v233
	v_add_f32_e32 v236, v234, v236
	v_add_f32_e32 v236, v235, v236
	global_store_dwordx4 v247, v[154:157], s[38:39]
	v_cvt_pk_bf16_f32 v232, v154, v155
	v_cvt_pk_bf16_f32 v233, v156, v157
	v_add_f32_dpp v236, v236, v236 quad_perm:[1,0,3,2] row_mask:0xf bank_mask:0xf
	global_store_dwordx2 v248, v[232:233], s[50:51]
	s_add_u32 s38, s38, 0x4000
	s_addc_u32 s39, s39, 0
	v_add_f32_dpp v236, v236, v236 quad_perm:[2,3,0,1] row_mask:0xf bank_mask:0xf
	s_add_u32 s50, s50, 0x2000
	s_addc_u32 s51, s51, 0
	v_add_f32_dpp v236, v236, v236 row_half_mirror row_mask:0xf bank_mask:0xf
	s_nop 1
	v_add_f32_dpp v236, v236, v236 row_mirror row_mask:0xf bank_mask:0xf
	s_mov_b64 exec, s[48:49]
	global_store_dword v249, v236, s[34:35] offset:1536
	s_mov_b64 exec, -1
	s_waitcnt vmcnt(45) lgkmcnt(1)
	v_pk_add_f32 v[158:159], v[238:239], v[158:159]
	v_pk_add_f32 v[160:161], v[240:241], v[160:161]
	v_pk_mul_f32 v[242:243], v[158:159], v[158:159]
	v_pk_mul_f32 v[244:245], v[160:161], v[160:161]
	ds_read_b128 v[238:241], v211 offset:9216
	v_add_f32_e32 v246, v242, v243
	v_add_f32_e32 v246, v244, v246
	v_add_f32_e32 v246, v245, v246
	global_store_dwordx4 v247, v[158:161], s[38:39]
	v_cvt_pk_bf16_f32 v242, v158, v159
	v_cvt_pk_bf16_f32 v243, v160, v161
	v_add_f32_dpp v246, v246, v246 quad_perm:[1,0,3,2] row_mask:0xf bank_mask:0xf
	global_store_dwordx2 v248, v[242:243], s[50:51]
	s_add_u32 s38, s38, 0x4000
	s_addc_u32 s39, s39, 0
	v_add_f32_dpp v246, v246, v246 quad_perm:[2,3,0,1] row_mask:0xf bank_mask:0xf
	s_add_u32 s50, s50, 0x2000
	s_addc_u32 s51, s51, 0
	v_add_f32_dpp v246, v246, v246 row_half_mirror row_mask:0xf bank_mask:0xf
	s_nop 1
	v_add_f32_dpp v246, v246, v246 row_mirror row_mask:0xf bank_mask:0xf
	s_mov_b64 exec, s[48:49]
	global_store_dword v249, v246, s[34:35] offset:1792
	s_mov_b64 exec, -1
	s_waitcnt vmcnt(47) lgkmcnt(1)
	v_pk_add_f32 v[162:163], v[228:229], v[162:163]
	v_pk_add_f32 v[164:165], v[230:231], v[164:165]
	v_pk_mul_f32 v[232:233], v[162:163], v[162:163]
	v_pk_mul_f32 v[234:235], v[164:165], v[164:165]
	ds_read_b128 v[228:231], v215 offset:10240
	v_add_f32_e32 v236, v232, v233
	v_add_f32_e32 v236, v234, v236
	v_add_f32_e32 v236, v235, v236
	global_store_dwordx4 v247, v[162:165], s[38:39]
	v_cvt_pk_bf16_f32 v232, v162, v163
	v_cvt_pk_bf16_f32 v233, v164, v165
	v_add_f32_dpp v236, v236, v236 quad_perm:[1,0,3,2] row_mask:0xf bank_mask:0xf
	global_store_dwordx2 v248, v[232:233], s[50:51]
	s_add_u32 s38, s38, 0x4000
	s_addc_u32 s39, s39, 0
	v_add_f32_dpp v236, v236, v236 quad_perm:[2,3,0,1] row_mask:0xf bank_mask:0xf
	s_add_u32 s50, s50, 0x2000
	s_addc_u32 s51, s51, 0
	v_add_f32_dpp v236, v236, v236 row_half_mirror row_mask:0xf bank_mask:0xf
	s_nop 1
	v_add_f32_dpp v236, v236, v236 row_mirror row_mask:0xf bank_mask:0xf
	s_mov_b64 exec, s[48:49]
	global_store_dword v249, v236, s[34:35] offset:2048
	s_mov_b64 exec, -1
	s_waitcnt vmcnt(49) lgkmcnt(1)
	v_pk_add_f32 v[166:167], v[238:239], v[166:167]
	v_pk_add_f32 v[168:169], v[240:241], v[168:169]
	v_pk_mul_f32 v[242:243], v[166:167], v[166:167]
	v_pk_mul_f32 v[244:245], v[168:169], v[168:169]
	ds_read_b128 v[238:241], v237 offset:11264
	v_add_f32_e32 v246, v242, v243
	v_add_f32_e32 v246, v244, v246
	v_add_f32_e32 v246, v245, v246
	global_store_dwordx4 v247, v[166:169], s[38:39]
	v_cvt_pk_bf16_f32 v242, v166, v167
	v_cvt_pk_bf16_f32 v243, v168, v169
	v_add_f32_dpp v246, v246, v246 quad_perm:[1,0,3,2] row_mask:0xf bank_mask:0xf
	global_store_dwordx2 v248, v[242:243], s[50:51]
	s_add_u32 s38, s38, 0x4000
	s_addc_u32 s39, s39, 0
	v_add_f32_dpp v246, v246, v246 quad_perm:[2,3,0,1] row_mask:0xf bank_mask:0xf
	s_add_u32 s50, s50, 0x2000
	s_addc_u32 s51, s51, 0
	v_add_f32_dpp v246, v246, v246 row_half_mirror row_mask:0xf bank_mask:0xf
	s_nop 1
	v_add_f32_dpp v246, v246, v246 row_mirror row_mask:0xf bank_mask:0xf
	s_mov_b64 exec, s[48:49]
	global_store_dword v249, v246, s[34:35] offset:2304
	s_mov_b64 exec, -1
	s_waitcnt vmcnt(51) lgkmcnt(1)
	v_pk_add_f32 v[192:193], v[228:229], v[192:193]
	v_pk_add_f32 v[194:195], v[230:231], v[194:195]
	v_pk_mul_f32 v[232:233], v[192:193], v[192:193]
	v_pk_mul_f32 v[234:235], v[194:195], v[194:195]
	ds_read_b128 v[228:231], v210 offset:12288
	v_add_f32_e32 v236, v232, v233
	v_add_f32_e32 v236, v234, v236
	v_add_f32_e32 v236, v235, v236
	global_store_dwordx4 v247, v[192:195], s[38:39]
	v_cvt_pk_bf16_f32 v232, v192, v193
	v_cvt_pk_bf16_f32 v233, v194, v195
	v_add_f32_dpp v236, v236, v236 quad_perm:[1,0,3,2] row_mask:0xf bank_mask:0xf
	global_store_dwordx2 v248, v[232:233], s[50:51]
	s_add_u32 s38, s38, 0x4000
	s_addc_u32 s39, s39, 0
	v_add_f32_dpp v236, v236, v236 quad_perm:[2,3,0,1] row_mask:0xf bank_mask:0xf
	s_add_u32 s50, s50, 0x2000
	s_addc_u32 s51, s51, 0
	v_add_f32_dpp v236, v236, v236 row_half_mirror row_mask:0xf bank_mask:0xf
	s_nop 1
	v_add_f32_dpp v236, v236, v236 row_mirror row_mask:0xf bank_mask:0xf
	s_mov_b64 exec, s[48:49]
	global_store_dword v249, v236, s[34:35] offset:2560
	s_mov_b64 exec, -1
	s_waitcnt vmcnt(53) lgkmcnt(1)
	v_pk_add_f32 v[196:197], v[238:239], v[196:197]
	v_pk_add_f32 v[198:199], v[240:241], v[198:199]
	v_pk_mul_f32 v[242:243], v[196:197], v[196:197]
	v_pk_mul_f32 v[244:245], v[198:199], v[198:199]
	ds_read_b128 v[238:241], v211 offset:13312
	v_add_f32_e32 v246, v242, v243
	v_add_f32_e32 v246, v244, v246
	v_add_f32_e32 v246, v245, v246
	global_store_dwordx4 v247, v[196:199], s[38:39]
	v_cvt_pk_bf16_f32 v242, v196, v197
	v_cvt_pk_bf16_f32 v243, v198, v199
	v_add_f32_dpp v246, v246, v246 quad_perm:[1,0,3,2] row_mask:0xf bank_mask:0xf
	global_store_dwordx2 v248, v[242:243], s[50:51]
	s_add_u32 s38, s38, 0x4000
	s_addc_u32 s39, s39, 0
	v_add_f32_dpp v246, v246, v246 quad_perm:[2,3,0,1] row_mask:0xf bank_mask:0xf
	s_add_u32 s50, s50, 0x2000
	s_addc_u32 s51, s51, 0
	v_add_f32_dpp v246, v246, v246 row_half_mirror row_mask:0xf bank_mask:0xf
	s_nop 1
	v_add_f32_dpp v246, v246, v246 row_mirror row_mask:0xf bank_mask:0xf
	s_mov_b64 exec, s[48:49]
	global_store_dword v249, v246, s[34:35] offset:2816
	s_mov_b64 exec, -1
	s_waitcnt vmcnt(55) lgkmcnt(1)
	v_pk_add_f32 v[200:201], v[228:229], v[200:201]
	v_pk_add_f32 v[202:203], v[230:231], v[202:203]
	v_pk_mul_f32 v[232:233], v[200:201], v[200:201]
	v_pk_mul_f32 v[234:235], v[202:203], v[202:203]
	ds_read_b128 v[228:231], v215 offset:14336
	v_add_f32_e32 v236, v232, v233
	v_add_f32_e32 v236, v234, v236
	v_add_f32_e32 v236, v235, v236
	global_store_dwordx4 v247, v[200:203], s[38:39]
	v_cvt_pk_bf16_f32 v232, v200, v201
	v_cvt_pk_bf16_f32 v233, v202, v203
	v_add_f32_dpp v236, v236, v236 quad_perm:[1,0,3,2] row_mask:0xf bank_mask:0xf
	global_store_dwordx2 v248, v[232:233], s[50:51]
	s_add_u32 s38, s38, 0x4000
	s_addc_u32 s39, s39, 0
	v_add_f32_dpp v236, v236, v236 quad_perm:[2,3,0,1] row_mask:0xf bank_mask:0xf
	s_add_u32 s50, s50, 0x2000
	s_addc_u32 s51, s51, 0
	v_add_f32_dpp v236, v236, v236 row_half_mirror row_mask:0xf bank_mask:0xf
	s_nop 1
	v_add_f32_dpp v236, v236, v236 row_mirror row_mask:0xf bank_mask:0xf
	s_mov_b64 exec, s[48:49]
	global_store_dword v249, v236, s[34:35] offset:3072
	s_mov_b64 exec, -1
	s_waitcnt vmcnt(57) lgkmcnt(1)
	v_pk_add_f32 v[216:217], v[238:239], v[216:217]
	v_pk_add_f32 v[218:219], v[240:241], v[218:219]
	v_pk_mul_f32 v[242:243], v[216:217], v[216:217]
	v_pk_mul_f32 v[244:245], v[218:219], v[218:219]
	ds_read_b128 v[238:241], v237 offset:15360
	v_add_f32_e32 v246, v242, v243
	v_add_f32_e32 v246, v244, v246
	v_add_f32_e32 v246, v245, v246
	global_store_dwordx4 v247, v[216:219], s[38:39]
	v_cvt_pk_bf16_f32 v242, v216, v217
	v_cvt_pk_bf16_f32 v243, v218, v219
	v_add_f32_dpp v246, v246, v246 quad_perm:[1,0,3,2] row_mask:0xf bank_mask:0xf
	global_store_dwordx2 v248, v[242:243], s[50:51]
	s_add_u32 s38, s38, 0x4000
	s_addc_u32 s39, s39, 0
	v_add_f32_dpp v246, v246, v246 quad_perm:[2,3,0,1] row_mask:0xf bank_mask:0xf
	s_add_u32 s50, s50, 0x2000
	s_addc_u32 s51, s51, 0
	v_add_f32_dpp v246, v246, v246 row_half_mirror row_mask:0xf bank_mask:0xf
	s_nop 1
	v_add_f32_dpp v246, v246, v246 row_mirror row_mask:0xf bank_mask:0xf
	s_mov_b64 exec, s[48:49]
	global_store_dword v249, v246, s[34:35] offset:3328
	s_mov_b64 exec, -1
	s_waitcnt vmcnt(59) lgkmcnt(1)
	v_pk_add_f32 v[220:221], v[228:229], v[220:221]
	v_pk_add_f32 v[222:223], v[230:231], v[222:223]
	v_pk_mul_f32 v[232:233], v[220:221], v[220:221]
	v_pk_mul_f32 v[234:235], v[222:223], v[222:223]
	v_add_f32_e32 v236, v232, v233
	v_add_f32_e32 v236, v234, v236
	v_add_f32_e32 v236, v235, v236
	global_store_dwordx4 v247, v[220:223], s[38:39]
	v_cvt_pk_bf16_f32 v232, v220, v221
	v_cvt_pk_bf16_f32 v233, v222, v223
	v_add_f32_dpp v236, v236, v236 quad_perm:[1,0,3,2] row_mask:0xf bank_mask:0xf
	global_store_dwordx2 v248, v[232:233], s[50:51]
	s_add_u32 s38, s38, 0x4000
	s_addc_u32 s39, s39, 0
	v_add_f32_dpp v236, v236, v236 quad_perm:[2,3,0,1] row_mask:0xf bank_mask:0xf
	s_add_u32 s50, s50, 0x2000
	s_addc_u32 s51, s51, 0
	v_add_f32_dpp v236, v236, v236 row_half_mirror row_mask:0xf bank_mask:0xf
	s_nop 1
	v_add_f32_dpp v236, v236, v236 row_mirror row_mask:0xf bank_mask:0xf
	s_mov_b64 exec, s[48:49]
	global_store_dword v249, v236, s[34:35] offset:3584
	s_mov_b64 exec, -1
	s_waitcnt vmcnt(61) lgkmcnt(0)
	v_pk_add_f32 v[224:225], v[238:239], v[224:225]
	v_pk_add_f32 v[226:227], v[240:241], v[226:227]
	v_pk_mul_f32 v[242:243], v[224:225], v[224:225]
	v_pk_mul_f32 v[244:245], v[226:227], v[226:227]
	v_add_f32_e32 v246, v242, v243
	v_add_f32_e32 v246, v244, v246
	v_add_f32_e32 v246, v245, v246
	global_store_dwordx4 v247, v[224:227], s[38:39]
	v_cvt_pk_bf16_f32 v242, v224, v225
	v_cvt_pk_bf16_f32 v243, v226, v227
	v_add_f32_dpp v246, v246, v246 quad_perm:[1,0,3,2] row_mask:0xf bank_mask:0xf
	global_store_dwordx2 v248, v[242:243], s[50:51]
	s_add_u32 s38, s38, 0x4000
	s_addc_u32 s39, s39, 0
	v_add_f32_dpp v246, v246, v246 quad_perm:[2,3,0,1] row_mask:0xf bank_mask:0xf
	s_add_u32 s50, s50, 0x2000
	s_addc_u32 s51, s51, 0
	v_add_f32_dpp v246, v246, v246 row_half_mirror row_mask:0xf bank_mask:0xf
	s_nop 1
	v_add_f32_dpp v246, v246, v246 row_mirror row_mask:0xf bank_mask:0xf
	s_mov_b64 exec, s[48:49]
	global_store_dword v249, v246, s[34:35] offset:3840
	s_mov_b64 exec, -1
	s_add_u32 s34, s34, 0x1000
	s_addc_u32 s35, s35, 0
	v_and_b32_e32 v238, 15, v170
	v_xor_b32_e32 v238, v238, v171
	v_lshl_add_u32 v239, v170, 8, s40
	v_xor_b32_e32 v228, 0, v238
	v_lshl_add_u32 v228, v228, 4, v239
	v_xor_b32_e32 v229, 2, v238
	v_lshl_add_u32 v229, v229, 4, v239
	v_xor_b32_e32 v230, 4, v238
	v_lshl_add_u32 v230, v230, 4, v239
	v_xor_b32_e32 v231, 6, v238
	v_lshl_add_u32 v231, v231, 4, v239
	v_xor_b32_e32 v232, 8, v238
	v_lshl_add_u32 v232, v232, 4, v239
	v_xor_b32_e32 v233, 10, v238
	v_lshl_add_u32 v233, v233, 4, v239
	v_xor_b32_e32 v234, 12, v238
	v_lshl_add_u32 v234, v234, 4, v239
	v_xor_b32_e32 v235, 14, v238
	v_lshl_add_u32 v235, v235, 4, v239
	ds_write_b128 v228, v[18:21]
	ds_write_b128 v229, v[22:25]
	ds_write_b128 v230, v[26:29]
	ds_write_b128 v231, v[30:33]
	ds_write_b128 v232, v[50:53]
	ds_write_b128 v233, v[54:57]
	ds_write_b128 v234, v[58:61]
	ds_write_b128 v235, v[62:65]
	ds_write_b128 v228, v[2:5] offset:8192
	ds_write_b128 v229, v[6:9] offset:8192
	ds_write_b128 v230, v[10:13] offset:8192
	ds_write_b128 v231, v[14:17] offset:8192
	ds_write_b128 v232, v[34:37] offset:8192
	ds_write_b128 v233, v[38:41] offset:8192
	ds_write_b128 v234, v[42:45] offset:8192
	ds_write_b128 v235, v[46:49] offset:8192
	s_waitcnt lgkmcnt(0)
	ds_read_b128 v[228:231], v210 offset:0
	ds_read_b128 v[238:241], v211 offset:1024
	s_waitcnt vmcnt(63) lgkmcnt(1)
	v_pk_add_f32 v[66:67], v[228:229], v[66:67]
	v_pk_add_f32 v[68:69], v[230:231], v[68:69]
	v_pk_mul_f32 v[232:233], v[66:67], v[66:67]
	v_pk_mul_f32 v[234:235], v[68:69], v[68:69]
	ds_read_b128 v[228:231], v215 offset:2048
	v_add_f32_e32 v236, v232, v233
	v_add_f32_e32 v236, v234, v236
	v_add_f32_e32 v236, v235, v236
	global_store_dwordx4 v247, v[66:69], s[38:39]
	v_cvt_pk_bf16_f32 v232, v66, v67
	v_cvt_pk_bf16_f32 v233, v68, v69
	v_add_f32_dpp v236, v236, v236 quad_perm:[1,0,3,2] row_mask:0xf bank_mask:0xf
	global_store_dwordx2 v248, v[232:233], s[50:51]
	s_add_u32 s38, s38, 0x4000
	s_addc_u32 s39, s39, 0
	v_add_f32_dpp v236, v236, v236 quad_perm:[2,3,0,1] row_mask:0xf bank_mask:0xf
	s_add_u32 s50, s50, 0x2000
	s_addc_u32 s51, s51, 0
	v_add_f32_dpp v236, v236, v236 row_half_mirror row_mask:0xf bank_mask:0xf
	s_nop 1
	v_add_f32_dpp v236, v236, v236 row_mirror row_mask:0xf bank_mask:0xf
	s_mov_b64 exec, s[48:49]
	global_store_dword v249, v236, s[34:35] offset:0
	s_mov_b64 exec, -1
	s_waitcnt vmcnt(63) lgkmcnt(1)
	v_pk_add_f32 v[70:71], v[238:239], v[70:71]
	v_pk_add_f32 v[72:73], v[240:241], v[72:73]
	v_pk_mul_f32 v[242:243], v[70:71], v[70:71]
	v_pk_mul_f32 v[244:245], v[72:73], v[72:73]
	ds_read_b128 v[238:241], v237 offset:3072
	v_add_f32_e32 v246, v242, v243
	v_add_f32_e32 v246, v244, v246
	v_add_f32_e32 v246, v245, v246
	global_store_dwordx4 v247, v[70:73], s[38:39]
	v_cvt_pk_bf16_f32 v242, v70, v71
	v_cvt_pk_bf16_f32 v243, v72, v73
	v_add_f32_dpp v246, v246, v246 quad_perm:[1,0,3,2] row_mask:0xf bank_mask:0xf
	global_store_dwordx2 v248, v[242:243], s[50:51]
	s_add_u32 s38, s38, 0x4000
	s_addc_u32 s39, s39, 0
	v_add_f32_dpp v246, v246, v246 quad_perm:[2,3,0,1] row_mask:0xf bank_mask:0xf
	s_add_u32 s50, s50, 0x2000
	s_addc_u32 s51, s51, 0
	v_add_f32_dpp v246, v246, v246 row_half_mirror row_mask:0xf bank_mask:0xf
	s_nop 1
	v_add_f32_dpp v246, v246, v246 row_mirror row_mask:0xf bank_mask:0xf
	s_mov_b64 exec, s[48:49]
	global_store_dword v249, v246, s[34:35] offset:256
	s_mov_b64 exec, -1
	s_waitcnt vmcnt(63) lgkmcnt(1)
	v_pk_add_f32 v[74:75], v[228:229], v[74:75]
	v_pk_add_f32 v[76:77], v[230:231], v[76:77]
	v_pk_mul_f32 v[232:233], v[74:75], v[74:75]
	v_pk_mul_f32 v[234:235], v[76:77], v[76:77]
	ds_read_b128 v[228:231], v210 offset:4096
	v_add_f32_e32 v236, v232, v233
	v_add_f32_e32 v236, v234, v236
	v_add_f32_e32 v236, v235, v236
	global_store_dwordx4 v247, v[74:77], s[38:39]
	v_cvt_pk_bf16_f32 v232, v74, v75
	v_cvt_pk_bf16_f32 v233, v76, v77
	v_add_f32_dpp v236, v236, v236 quad_perm:[1,0,3,2] row_mask:0xf bank_mask:0xf
	global_store_dwordx2 v248, v[232:233], s[50:51]
	s_add_u32 s38, s38, 0x4000
	s_addc_u32 s39, s39, 0
	v_add_f32_dpp v236, v236, v236 quad_perm:[2,3,0,1] row_mask:0xf bank_mask:0xf
	s_add_u32 s50, s50, 0x2000
	s_addc_u32 s51, s51, 0
	v_add_f32_dpp v236, v236, v236 row_half_mirror row_mask:0xf bank_mask:0xf
	s_nop 1
	v_add_f32_dpp v236, v236, v236 row_mirror row_mask:0xf bank_mask:0xf
	s_mov_b64 exec, s[48:49]
	global_store_dword v249, v236, s[34:35] offset:512
	s_mov_b64 exec, -1
	s_waitcnt vmcnt(63) lgkmcnt(1)
	v_pk_add_f32 v[78:79], v[238:239], v[78:79]
	v_pk_add_f32 v[80:81], v[240:241], v[80:81]
	v_pk_mul_f32 v[242:243], v[78:79], v[78:79]
	v_pk_mul_f32 v[244:245], v[80:81], v[80:81]
	ds_read_b128 v[238:241], v211 offset:5120
	v_add_f32_e32 v246, v242, v243
	v_add_f32_e32 v246, v244, v246
	v_add_f32_e32 v246, v245, v246
	global_store_dwordx4 v247, v[78:81], s[38:39]
	v_cvt_pk_bf16_f32 v242, v78, v79
	v_cvt_pk_bf16_f32 v243, v80, v81
	v_add_f32_dpp v246, v246, v246 quad_perm:[1,0,3,2] row_mask:0xf bank_mask:0xf
	global_store_dwordx2 v248, v[242:243], s[50:51]
	s_add_u32 s38, s38, 0x4000
	s_addc_u32 s39, s39, 0
	v_add_f32_dpp v246, v246, v246 quad_perm:[2,3,0,1] row_mask:0xf bank_mask:0xf
	s_add_u32 s50, s50, 0x2000
	s_addc_u32 s51, s51, 0
	v_add_f32_dpp v246, v246, v246 row_half_mirror row_mask:0xf bank_mask:0xf
	s_nop 1
	v_add_f32_dpp v246, v246, v246 row_mirror row_mask:0xf bank_mask:0xf
	s_mov_b64 exec, s[48:49]
	global_store_dword v249, v246, s[34:35] offset:768
	s_mov_b64 exec, -1
	s_waitcnt vmcnt(63) lgkmcnt(1)
	v_pk_add_f32 v[114:115], v[228:229], v[114:115]
	v_pk_add_f32 v[116:117], v[230:231], v[116:117]
	v_pk_mul_f32 v[232:233], v[114:115], v[114:115]
	v_pk_mul_f32 v[234:235], v[116:117], v[116:117]
	ds_read_b128 v[228:231], v215 offset:6144
	v_add_f32_e32 v236, v232, v233
	v_add_f32_e32 v236, v234, v236
	v_add_f32_e32 v236, v235, v236
	global_store_dwordx4 v247, v[114:117], s[38:39]
	v_cvt_pk_bf16_f32 v232, v114, v115
	v_cvt_pk_bf16_f32 v233, v116, v117
	v_add_f32_dpp v236, v236, v236 quad_perm:[1,0,3,2] row_mask:0xf bank_mask:0xf
	global_store_dwordx2 v248, v[232:233], s[50:51]
	s_add_u32 s38, s38, 0x4000
	s_addc_u32 s39, s39, 0
	v_add_f32_dpp v236, v236, v236 quad_perm:[2,3,0,1] row_mask:0xf bank_mask:0xf
	s_add_u32 s50, s50, 0x2000
	s_addc_u32 s51, s51, 0
	v_add_f32_dpp v236, v236, v236 row_half_mirror row_mask:0xf bank_mask:0xf
	s_nop 1
	v_add_f32_dpp v236, v236, v236 row_mirror row_mask:0xf bank_mask:0xf
	s_mov_b64 exec, s[48:49]
	global_store_dword v249, v236, s[34:35] offset:1024
	s_mov_b64 exec, -1
	s_waitcnt vmcnt(63) lgkmcnt(1)
	v_pk_add_f32 v[118:119], v[238:239], v[118:119]
	v_pk_add_f32 v[120:121], v[240:241], v[120:121]
	v_pk_mul_f32 v[242:243], v[118:119], v[118:119]
	v_pk_mul_f32 v[244:245], v[120:121], v[120:121]
	ds_read_b128 v[238:241], v237 offset:7168
	v_add_f32_e32 v246, v242, v243
	v_add_f32_e32 v246, v244, v246
	v_add_f32_e32 v246, v245, v246
	global_store_dwordx4 v247, v[118:121], s[38:39]
	v_cvt_pk_bf16_f32 v242, v118, v119
	v_cvt_pk_bf16_f32 v243, v120, v121
	v_add_f32_dpp v246, v246, v246 quad_perm:[1,0,3,2] row_mask:0xf bank_mask:0xf
	global_store_dwordx2 v248, v[242:243], s[50:51]
	s_add_u32 s38, s38, 0x4000
	s_addc_u32 s39, s39, 0
	v_add_f32_dpp v246, v246, v246 quad_perm:[2,3,0,1] row_mask:0xf bank_mask:0xf
	s_add_u32 s50, s50, 0x2000
	s_addc_u32 s51, s51, 0
	v_add_f32_dpp v246, v246, v246 row_half_mirror row_mask:0xf bank_mask:0xf
	s_nop 1
	v_add_f32_dpp v246, v246, v246 row_mirror row_mask:0xf bank_mask:0xf
	s_mov_b64 exec, s[48:49]
	global_store_dword v249, v246, s[34:35] offset:1280
	s_mov_b64 exec, -1
	s_waitcnt vmcnt(63) lgkmcnt(1)
	v_pk_add_f32 v[122:123], v[228:229], v[122:123]
	v_pk_add_f32 v[124:125], v[230:231], v[124:125]
	v_pk_mul_f32 v[232:233], v[122:123], v[122:123]
	v_pk_mul_f32 v[234:235], v[124:125], v[124:125]
	ds_read_b128 v[228:231], v210 offset:8192
	v_add_f32_e32 v236, v232, v233
	v_add_f32_e32 v236, v234, v236
	v_add_f32_e32 v236, v235, v236
	global_store_dwordx4 v247, v[122:125], s[38:39]
	v_cvt_pk_bf16_f32 v232, v122, v123
	v_cvt_pk_bf16_f32 v233, v124, v125
	v_add_f32_dpp v236, v236, v236 quad_perm:[1,0,3,2] row_mask:0xf bank_mask:0xf
	global_store_dwordx2 v248, v[232:233], s[50:51]
	s_add_u32 s38, s38, 0x4000
	s_addc_u32 s39, s39, 0
	v_add_f32_dpp v236, v236, v236 quad_perm:[2,3,0,1] row_mask:0xf bank_mask:0xf
	s_add_u32 s50, s50, 0x2000
	s_addc_u32 s51, s51, 0
	v_add_f32_dpp v236, v236, v236 row_half_mirror row_mask:0xf bank_mask:0xf
	s_nop 1
	v_add_f32_dpp v236, v236, v236 row_mirror row_mask:0xf bank_mask:0xf
	s_mov_b64 exec, s[48:49]
	global_store_dword v249, v236, s[34:35] offset:1536
	s_mov_b64 exec, -1
	s_waitcnt vmcnt(63) lgkmcnt(1)
	v_pk_add_f32 v[126:127], v[238:239], v[126:127]
	v_pk_add_f32 v[128:129], v[240:241], v[128:129]
	v_pk_mul_f32 v[242:243], v[126:127], v[126:127]
	v_pk_mul_f32 v[244:245], v[128:129], v[128:129]
	ds_read_b128 v[238:241], v211 offset:9216
	v_add_f32_e32 v246, v242, v243
	v_add_f32_e32 v246, v244, v246
	v_add_f32_e32 v246, v245, v246
	global_store_dwordx4 v247, v[126:129], s[38:39]
	v_cvt_pk_bf16_f32 v242, v126, v127
	v_cvt_pk_bf16_f32 v243, v128, v129
	v_add_f32_dpp v246, v246, v246 quad_perm:[1,0,3,2] row_mask:0xf bank_mask:0xf
	global_store_dwordx2 v248, v[242:243], s[50:51]
	s_add_u32 s38, s38, 0x4000
	s_addc_u32 s39, s39, 0
	v_add_f32_dpp v246, v246, v246 quad_perm:[2,3,0,1] row_mask:0xf bank_mask:0xf
	s_add_u32 s50, s50, 0x2000
	s_addc_u32 s51, s51, 0
	v_add_f32_dpp v246, v246, v246 row_half_mirror row_mask:0xf bank_mask:0xf
	s_nop 1
	v_add_f32_dpp v246, v246, v246 row_mirror row_mask:0xf bank_mask:0xf
	s_mov_b64 exec, s[48:49]
	global_store_dword v249, v246, s[34:35] offset:1792
	s_mov_b64 exec, -1
	s_waitcnt vmcnt(63) lgkmcnt(1)
	v_pk_add_f32 v[82:83], v[228:229], v[82:83]
	v_pk_add_f32 v[84:85], v[230:231], v[84:85]
	v_pk_mul_f32 v[232:233], v[82:83], v[82:83]
	v_pk_mul_f32 v[234:235], v[84:85], v[84:85]
	ds_read_b128 v[228:231], v215 offset:10240
	v_add_f32_e32 v236, v232, v233
	v_add_f32_e32 v236, v234, v236
	v_add_f32_e32 v236, v235, v236
	global_store_dwordx4 v247, v[82:85], s[38:39]
	v_cvt_pk_bf16_f32 v232, v82, v83
	v_cvt_pk_bf16_f32 v233, v84, v85
	v_add_f32_dpp v236, v236, v236 quad_perm:[1,0,3,2] row_mask:0xf bank_mask:0xf
	global_store_dwordx2 v248, v[232:233], s[50:51]
	s_add_u32 s38, s38, 0x4000
	s_addc_u32 s39, s39, 0
	v_add_f32_dpp v236, v236, v236 quad_perm:[2,3,0,1] row_mask:0xf bank_mask:0xf
	s_add_u32 s50, s50, 0x2000
	s_addc_u32 s51, s51, 0
	v_add_f32_dpp v236, v236, v236 row_half_mirror row_mask:0xf bank_mask:0xf
	s_nop 1
	v_add_f32_dpp v236, v236, v236 row_mirror row_mask:0xf bank_mask:0xf
	s_mov_b64 exec, s[48:49]
	global_store_dword v249, v236, s[34:35] offset:2048
	s_mov_b64 exec, -1
	s_waitcnt vmcnt(63) lgkmcnt(1)
	v_pk_add_f32 v[86:87], v[238:239], v[86:87]
	v_pk_add_f32 v[88:89], v[240:241], v[88:89]
	v_pk_mul_f32 v[242:243], v[86:87], v[86:87]
	v_pk_mul_f32 v[244:245], v[88:89], v[88:89]
	ds_read_b128 v[238:241], v237 offset:11264
	v_add_f32_e32 v246, v242, v243
	v_add_f32_e32 v246, v244, v246
	v_add_f32_e32 v246, v245, v246
	global_store_dwordx4 v247, v[86:89], s[38:39]
	v_cvt_pk_bf16_f32 v242, v86, v87
	v_cvt_pk_bf16_f32 v243, v88, v89
	v_add_f32_dpp v246, v246, v246 quad_perm:[1,0,3,2] row_mask:0xf bank_mask:0xf
	global_store_dwordx2 v248, v[242:243], s[50:51]
	s_add_u32 s38, s38, 0x4000
	s_addc_u32 s39, s39, 0
	v_add_f32_dpp v246, v246, v246 quad_perm:[2,3,0,1] row_mask:0xf bank_mask:0xf
	s_add_u32 s50, s50, 0x2000
	s_addc_u32 s51, s51, 0
	v_add_f32_dpp v246, v246, v246 row_half_mirror row_mask:0xf bank_mask:0xf
	s_nop 1
	v_add_f32_dpp v246, v246, v246 row_mirror row_mask:0xf bank_mask:0xf
	s_mov_b64 exec, s[48:49]
	global_store_dword v249, v246, s[34:35] offset:2304
	s_mov_b64 exec, -1
	s_waitcnt vmcnt(63) lgkmcnt(1)
	v_pk_add_f32 v[90:91], v[228:229], v[90:91]
	v_pk_add_f32 v[92:93], v[230:231], v[92:93]
	v_pk_mul_f32 v[232:233], v[90:91], v[90:91]
	v_pk_mul_f32 v[234:235], v[92:93], v[92:93]
	ds_read_b128 v[228:231], v210 offset:12288
	v_add_f32_e32 v236, v232, v233
	v_add_f32_e32 v236, v234, v236
	v_add_f32_e32 v236, v235, v236
	global_store_dwordx4 v247, v[90:93], s[38:39]
	v_cvt_pk_bf16_f32 v232, v90, v91
	v_cvt_pk_bf16_f32 v233, v92, v93
	v_add_f32_dpp v236, v236, v236 quad_perm:[1,0,3,2] row_mask:0xf bank_mask:0xf
	global_store_dwordx2 v248, v[232:233], s[50:51]
	s_add_u32 s38, s38, 0x4000
	s_addc_u32 s39, s39, 0
	v_add_f32_dpp v236, v236, v236 quad_perm:[2,3,0,1] row_mask:0xf bank_mask:0xf
	s_add_u32 s50, s50, 0x2000
	s_addc_u32 s51, s51, 0
	v_add_f32_dpp v236, v236, v236 row_half_mirror row_mask:0xf bank_mask:0xf
	s_nop 1
	v_add_f32_dpp v236, v236, v236 row_mirror row_mask:0xf bank_mask:0xf
	s_mov_b64 exec, s[48:49]
	global_store_dword v249, v236, s[34:35] offset:2560
	s_mov_b64 exec, -1
	s_waitcnt vmcnt(63) lgkmcnt(1)
	v_pk_add_f32 v[94:95], v[238:239], v[94:95]
	v_pk_add_f32 v[96:97], v[240:241], v[96:97]
	v_pk_mul_f32 v[242:243], v[94:95], v[94:95]
	v_pk_mul_f32 v[244:245], v[96:97], v[96:97]
	ds_read_b128 v[238:241], v211 offset:13312
	v_add_f32_e32 v246, v242, v243
	v_add_f32_e32 v246, v244, v246
	v_add_f32_e32 v246, v245, v246
	global_store_dwordx4 v247, v[94:97], s[38:39]
	v_cvt_pk_bf16_f32 v242, v94, v95
	v_cvt_pk_bf16_f32 v243, v96, v97
	v_add_f32_dpp v246, v246, v246 quad_perm:[1,0,3,2] row_mask:0xf bank_mask:0xf
	global_store_dwordx2 v248, v[242:243], s[50:51]
	s_add_u32 s38, s38, 0x4000
	s_addc_u32 s39, s39, 0
	v_add_f32_dpp v246, v246, v246 quad_perm:[2,3,0,1] row_mask:0xf bank_mask:0xf
	s_add_u32 s50, s50, 0x2000
	s_addc_u32 s51, s51, 0
	v_add_f32_dpp v246, v246, v246 row_half_mirror row_mask:0xf bank_mask:0xf
	s_nop 1
	v_add_f32_dpp v246, v246, v246 row_mirror row_mask:0xf bank_mask:0xf
	s_mov_b64 exec, s[48:49]
	global_store_dword v249, v246, s[34:35] offset:2816
	s_mov_b64 exec, -1
	s_waitcnt vmcnt(63) lgkmcnt(1)
	v_pk_add_f32 v[98:99], v[228:229], v[98:99]
	v_pk_add_f32 v[100:101], v[230:231], v[100:101]
	v_pk_mul_f32 v[232:233], v[98:99], v[98:99]
	v_pk_mul_f32 v[234:235], v[100:101], v[100:101]
	ds_read_b128 v[228:231], v215 offset:14336
	v_add_f32_e32 v236, v232, v233
	v_add_f32_e32 v236, v234, v236
	v_add_f32_e32 v236, v235, v236
	global_store_dwordx4 v247, v[98:101], s[38:39]
	v_cvt_pk_bf16_f32 v232, v98, v99
	v_cvt_pk_bf16_f32 v233, v100, v101
	v_add_f32_dpp v236, v236, v236 quad_perm:[1,0,3,2] row_mask:0xf bank_mask:0xf
	global_store_dwordx2 v248, v[232:233], s[50:51]
	s_add_u32 s38, s38, 0x4000
	s_addc_u32 s39, s39, 0
	v_add_f32_dpp v236, v236, v236 quad_perm:[2,3,0,1] row_mask:0xf bank_mask:0xf
	s_add_u32 s50, s50, 0x2000
	s_addc_u32 s51, s51, 0
	v_add_f32_dpp v236, v236, v236 row_half_mirror row_mask:0xf bank_mask:0xf
	s_nop 1
	v_add_f32_dpp v236, v236, v236 row_mirror row_mask:0xf bank_mask:0xf
	s_mov_b64 exec, s[48:49]
	global_store_dword v249, v236, s[34:35] offset:3072
	s_mov_b64 exec, -1
	s_waitcnt vmcnt(63) lgkmcnt(1)
	v_pk_add_f32 v[102:103], v[238:239], v[102:103]
	v_pk_add_f32 v[104:105], v[240:241], v[104:105]
	v_pk_mul_f32 v[242:243], v[102:103], v[102:103]
	v_pk_mul_f32 v[244:245], v[104:105], v[104:105]
	ds_read_b128 v[238:241], v237 offset:15360
	v_add_f32_e32 v246, v242, v243
	v_add_f32_e32 v246, v244, v246
	v_add_f32_e32 v246, v245, v246
	global_store_dwordx4 v247, v[102:105], s[38:39]
	v_cvt_pk_bf16_f32 v242, v102, v103
	v_cvt_pk_bf16_f32 v243, v104, v105
	v_add_f32_dpp v246, v246, v246 quad_perm:[1,0,3,2] row_mask:0xf bank_mask:0xf
	global_store_dwordx2 v248, v[242:243], s[50:51]
	s_add_u32 s38, s38, 0x4000
	s_addc_u32 s39, s39, 0
	v_add_f32_dpp v246, v246, v246 quad_perm:[2,3,0,1] row_mask:0xf bank_mask:0xf
	s_add_u32 s50, s50, 0x2000
	s_addc_u32 s51, s51, 0
	v_add_f32_dpp v246, v246, v246 row_half_mirror row_mask:0xf bank_mask:0xf
	s_nop 1
	v_add_f32_dpp v246, v246, v246 row_mirror row_mask:0xf bank_mask:0xf
	s_mov_b64 exec, s[48:49]
	global_store_dword v249, v246, s[34:35] offset:3328
	s_mov_b64 exec, -1
	s_waitcnt vmcnt(63) lgkmcnt(1)
	v_pk_add_f32 v[106:107], v[228:229], v[106:107]
	v_pk_add_f32 v[108:109], v[230:231], v[108:109]
	v_pk_mul_f32 v[232:233], v[106:107], v[106:107]
	v_pk_mul_f32 v[234:235], v[108:109], v[108:109]
	v_add_f32_e32 v236, v232, v233
	v_add_f32_e32 v236, v234, v236
	v_add_f32_e32 v236, v235, v236
	global_store_dwordx4 v247, v[106:109], s[38:39]
	v_cvt_pk_bf16_f32 v232, v106, v107
	v_cvt_pk_bf16_f32 v233, v108, v109
	v_add_f32_dpp v236, v236, v236 quad_perm:[1,0,3,2] row_mask:0xf bank_mask:0xf
	global_store_dwordx2 v248, v[232:233], s[50:51]
	s_add_u32 s38, s38, 0x4000
	s_addc_u32 s39, s39, 0
	v_add_f32_dpp v236, v236, v236 quad_perm:[2,3,0,1] row_mask:0xf bank_mask:0xf
	s_add_u32 s50, s50, 0x2000
	s_addc_u32 s51, s51, 0
	v_add_f32_dpp v236, v236, v236 row_half_mirror row_mask:0xf bank_mask:0xf
	s_nop 1
	v_add_f32_dpp v236, v236, v236 row_mirror row_mask:0xf bank_mask:0xf
	s_mov_b64 exec, s[48:49]
	global_store_dword v249, v236, s[34:35] offset:3584
	s_mov_b64 exec, -1
	s_waitcnt vmcnt(63) lgkmcnt(0)
	v_pk_add_f32 v[110:111], v[238:239], v[110:111]
	v_pk_add_f32 v[112:113], v[240:241], v[112:113]
	v_pk_mul_f32 v[242:243], v[110:111], v[110:111]
	v_pk_mul_f32 v[244:245], v[112:113], v[112:113]
	v_add_f32_e32 v246, v242, v243
	v_add_f32_e32 v246, v244, v246
	v_add_f32_e32 v246, v245, v246
	global_store_dwordx4 v247, v[110:113], s[38:39]
	v_cvt_pk_bf16_f32 v242, v110, v111
	v_cvt_pk_bf16_f32 v243, v112, v113
	v_add_f32_dpp v246, v246, v246 quad_perm:[1,0,3,2] row_mask:0xf bank_mask:0xf
	global_store_dwordx2 v248, v[242:243], s[50:51]
	s_add_u32 s38, s38, 0x4000
	s_addc_u32 s39, s39, 0
	v_add_f32_dpp v246, v246, v246 quad_perm:[2,3,0,1] row_mask:0xf bank_mask:0xf
	s_add_u32 s50, s50, 0x2000
	s_addc_u32 s51, s51, 0
	v_add_f32_dpp v246, v246, v246 row_half_mirror row_mask:0xf bank_mask:0xf
	s_nop 1
	v_add_f32_dpp v246, v246, v246 row_mirror row_mask:0xf bank_mask:0xf
	s_mov_b64 exec, s[48:49]
	global_store_dword v249, v246, s[34:35] offset:3840
	s_mov_b64 exec, -1
	s_waitcnt lgkmcnt(0)
	s_branch .LBB0_1677
.Lres_mlp2_last:
	v_readfirstlane_b32 s40, v204
	s_lshr_b32 s40, s40, 6
	s_and_b32 s41, s40, 1
	s_bfe_u32 s42, s40, 0x10001
	s_lshr_b32 s43, s40, 2
	s_lshl_b32 s44, s4, 1
	s_add_i32 s44, s44, s42
	s_lshl_b32 s45, s44, 7
	s_lshl_b32 s46, s41, 6
	s_add_i32 s45, s45, s46
	s_lshl_b32 s46, s43, 7
	s_add_i32 s46, s46, s2
	s_lshl_b32 s47, s44, 1
	s_add_i32 s47, s47, s41
	v_readlane_b32 s36, v250, 9
	v_readlane_b32 s37, v250, 10
	s_mov_b64 s[38:39], s[36:37]
	v_readlane_b32 s50, v250, 11
	v_readlane_b32 s51, v250, 12
	s_add_u32 s34, s50, 0xf900000
	s_addc_u32 s35, s51, 0
	s_add_u32 s50, s50, 0x5800000
	s_addc_u32 s51, s51, 0
	s_lshl_b32 s48, s46, 12
	s_lshl_b32 s49, s45, 2
	s_add_u32 s48, s48, s49
	s_add_u32 s36, s36, s48
	s_addc_u32 s37, s37, 0
	s_add_u32 s38, s38, s48
	s_addc_u32 s39, s39, 0
	s_lshr_b32 s48, s48, 1
	s_add_u32 s50, s50, s48
	s_addc_u32 s51, s51, 0
	s_lshl_b32 s48, s46, 6
	s_lshl_b32 s49, s47, 2
	s_add_u32 s48, s48, s49
	s_add_u32 s34, s34, s48
	s_addc_u32 s35, s35, 0
	v_and_b32_e32 v249, 63, v204
	v_and_b32_e32 v170, 31, v249
	v_lshrrev_b32_e32 v171, 5, v249
	v_and_b32_e32 v208, 15, v249
	v_lshrrev_b32_e32 v209, 4, v249
	s_lshl_b32 s40, s40, 14
	v_and_b32_e32 v238, 15, v170
	v_xor_b32_e32 v238, v238, v171
	v_lshl_add_u32 v239, v170, 8, s40
	v_xor_b32_e32 v228, 0, v238
	v_lshl_add_u32 v228, v228, 4, v239
	v_xor_b32_e32 v229, 2, v238
	v_lshl_add_u32 v229, v229, 4, v239
	v_xor_b32_e32 v230, 4, v238
	v_lshl_add_u32 v230, v230, 4, v239
	v_xor_b32_e32 v231, 6, v238
	v_lshl_add_u32 v231, v231, 4, v239
	v_xor_b32_e32 v232, 8, v238
	v_lshl_add_u32 v232, v232, 4, v239
	v_xor_b32_e32 v233, 10, v238
	v_lshl_add_u32 v233, v233, 4, v239
	v_xor_b32_e32 v234, 12, v238
	v_lshl_add_u32 v234, v234, 4, v239
	v_xor_b32_e32 v235, 14, v238
	v_lshl_add_u32 v235, v235, 4, v239
	v_lshl_add_u32 v239, v209, 8, s40
	v_add_u32_e32 v210, 0, v209
	v_xor_b32_e32 v210, v210, v208
	v_lshl_add_u32 v210, v210, 4, v239
	v_add_u32_e32 v211, 4, v209
	v_xor_b32_e32 v211, v211, v208
	v_lshl_add_u32 v211, v211, 4, v239
	v_add_u32_e32 v215, 8, v209
	v_xor_b32_e32 v215, v215, v208
	v_lshl_add_u32 v215, v215, 4, v239
	v_add_u32_e32 v237, 12, v209
	v_xor_b32_e32 v237, v237, v208
	v_lshl_add_u32 v237, v237, 4, v239
	v_lshlrev_b32_e32 v247, 12, v209
	v_lshl_add_u32 v247, v208, 4, v247
	v_lshrrev_b32_e32 v248, 1, v247
	v_lshlrev_b32_e32 v249, 6, v209
	s_mov_b32 s48, 0x00010001
	s_mov_b32 s49, 0x00010001
	global_load_dwordx4 v[130:133], v247, s[36:37]
	s_add_u32 s36, s36, 0x4000
	s_addc_u32 s37, s37, 0
	global_load_dwordx4 v[134:137], v247, s[36:37]
	s_add_u32 s36, s36, 0x4000
	s_addc_u32 s37, s37, 0
	global_load_dwordx4 v[138:141], v247, s[36:37]
	s_add_u32 s36, s36, 0x4000
	s_addc_u32 s37, s37, 0
	global_load_dwordx4 v[142:145], v247, s[36:37]
	s_add_u32 s36, s36, 0x4000
	s_addc_u32 s37, s37, 0
	global_load_dwordx4 v[146:149], v247, s[36:37]
	s_add_u32 s36, s36, 0x4000
	s_addc_u32 s37, s37, 0
	global_load_dwordx4 v[150:153], v247, s[36:37]
	s_add_u32 s36, s36, 0x4000
	s_addc_u32 s37, s37, 0
	global_load_dwordx4 v[154:157], v247, s[36:37]
	s_add_u32 s36, s36, 0x4000
	s_addc_u32 s37, s37, 0
	global_load_dwordx4 v[158:161], v247, s[36:37]
	s_add_u32 s36, s36, 0x4000
	s_addc_u32 s37, s37, 0
	global_load_dwordx4 v[162:165], v247, s[36:37]
	s_add_u32 s36, s36, 0x4000
	s_addc_u32 s37, s37, 0
	global_load_dwordx4 v[166:169], v247, s[36:37]
	s_add_u32 s36, s36, 0x4000
	s_addc_u32 s37, s37, 0
	global_load_dwordx4 v[192:195], v247, s[36:37]
	s_add_u32 s36, s36, 0x4000
	s_addc_u32 s37, s37, 0
	global_load_dwordx4 v[196:199], v247, s[36:37]
	s_add_u32 s36, s36, 0x4000
	s_addc_u32 s37, s37, 0
	global_load_dwordx4 v[200:203], v247, s[36:37]
	s_add_u32 s36, s36, 0x4000
	s_addc_u32 s37, s37, 0
	global_load_dwordx4 v[216:219], v247, s[36:37]
	s_add_u32 s36, s36, 0x4000
	s_addc_u32 s37, s37, 0
	global_load_dwordx4 v[220:223], v247, s[36:37]
	s_add_u32 s36, s36, 0x4000
	s_addc_u32 s37, s37, 0
	global_load_dwordx4 v[224:227], v247, s[36:37]
	s_add_u32 s36, s36, 0x4000
	s_addc_u32 s37, s37, 0
	ds_write_b128 v228, v[66:69]
	ds_write_b128 v229, v[70:73]
	ds_write_b128 v230, v[74:77]
	ds_write_b128 v231, v[78:81]
	ds_write_b128 v232, v[114:117]
	ds_write_b128 v233, v[118:121]
	ds_write_b128 v234, v[122:125]
	ds_write_b128 v235, v[126:129]
	ds_write_b128 v228, v[82:85] offset:8192
	ds_write_b128 v229, v[86:89] offset:8192
	ds_write_b128 v230, v[90:93] offset:8192
	ds_write_b128 v231, v[94:97] offset:8192
	ds_write_b128 v232, v[98:101] offset:8192
	ds_write_b128 v233, v[102:105] offset:8192
	ds_write_b128 v234, v[106:109] offset:8192
	ds_write_b128 v235, v[110:113] offset:8192
	global_load_dwordx4 v[66:69], v247, s[36:37]
	s_add_u32 s36, s36, 0x4000
	s_addc_u32 s37, s37, 0
	global_load_dwordx4 v[70:73], v247, s[36:37]
	s_add_u32 s36, s36, 0x4000
	s_addc_u32 s37, s37, 0
	global_load_dwordx4 v[74:77], v247, s[36:37]
	s_add_u32 s36, s36, 0x4000
	s_addc_u32 s37, s37, 0
	global_load_dwordx4 v[78:81], v247, s[36:37]
	s_add_u32 s36, s36, 0x4000
	s_addc_u32 s37, s37, 0
	global_load_dwordx4 v[114:117], v247, s[36:37]
	s_add_u32 s36, s36, 0x4000
	s_addc_u32 s37, s37, 0
	global_load_dwordx4 v[118:121], v247, s[36:37]
	s_add_u32 s36, s36, 0x4000
	s_addc_u32 s37, s37, 0
	global_load_dwordx4 v[122:125], v247, s[36:37]
	s_add_u32 s36, s36, 0x4000
	s_addc_u32 s37, s37, 0
	global_load_dwordx4 v[126:129], v247, s[36:37]
	s_add_u32 s36, s36, 0x4000
	s_addc_u32 s37, s37, 0
	global_load_dwordx4 v[82:85], v247, s[36:37]
	s_add_u32 s36, s36, 0x4000
	s_addc_u32 s37, s37, 0
	global_load_dwordx4 v[86:89], v247, s[36:37]
	s_add_u32 s36, s36, 0x4000
	s_addc_u32 s37, s37, 0
	global_load_dwordx4 v[90:93], v247, s[36:37]
	s_add_u32 s36, s36, 0x4000
	s_addc_u32 s37, s37, 0
	global_load_dwordx4 v[94:97], v247, s[36:37]
	s_add_u32 s36, s36, 0x4000
	s_addc_u32 s37, s37, 0
	global_load_dwordx4 v[98:101], v247, s[36:37]
	s_add_u32 s36, s36, 0x4000
	s_addc_u32 s37, s37, 0
	global_load_dwordx4 v[102:105], v247, s[36:37]
	s_add_u32 s36, s36, 0x4000
	s_addc_u32 s37, s37, 0
	global_load_dwordx4 v[106:109], v247, s[36:37]
	s_add_u32 s36, s36, 0x4000
	s_addc_u32 s37, s37, 0
	global_load_dwordx4 v[110:113], v247, s[36:37]
	s_add_u32 s36, s36, 0x4000
	s_addc_u32 s37, s37, 0
	s_waitcnt lgkmcnt(0)
	ds_read_b128 v[228:231], v210 offset:0
	ds_read_b128 v[238:241], v211 offset:1024
	s_waitcnt vmcnt(31) lgkmcnt(1)
	v_pk_add_f32 v[130:131], v[228:229], v[130:131]
	v_pk_add_f32 v[132:133], v[230:231], v[132:133]
	ds_read_b128 v[228:231], v215 offset:2048
	global_store_dwordx4 v247, v[130:133], s[38:39]
	s_add_u32 s38, s38, 0x4000
	s_addc_u32 s39, s39, 0
	s_waitcnt vmcnt(31) lgkmcnt(1)
	v_pk_add_f32 v[134:135], v[238:239], v[134:135]
	v_pk_add_f32 v[136:137], v[240:241], v[136:137]
	ds_read_b128 v[238:241], v237 offset:3072
	global_store_dwordx4 v247, v[134:137], s[38:39]
	s_add_u32 s38, s38, 0x4000
	s_addc_u32 s39, s39, 0
	s_waitcnt vmcnt(31) lgkmcnt(1)
	v_pk_add_f32 v[138:139], v[228:229], v[138:139]
	v_pk_add_f32 v[140:141], v[230:231], v[140:141]
	ds_read_b128 v[228:231], v210 offset:4096
	global_store_dwordx4 v247, v[138:141], s[38:39]
	s_add_u32 s38, s38, 0x4000
	s_addc_u32 s39, s39, 0
	s_waitcnt vmcnt(31) lgkmcnt(1)
	v_pk_add_f32 v[142:143], v[238:239], v[142:143]
	v_pk_add_f32 v[144:145], v[240:241], v[144:145]
	ds_read_b128 v[238:241], v211 offset:5120
	global_store_dwordx4 v247, v[142:145], s[38:39]
	s_add_u32 s38, s38, 0x4000
	s_addc_u32 s39, s39, 0
	s_waitcnt vmcnt(31) lgkmcnt(1)
	v_pk_add_f32 v[146:147], v[228:229], v[146:147]
	v_pk_add_f32 v[148:149], v[230:231], v[148:149]
	ds_read_b128 v[228:231], v215 offset:6144
	global_store_dwordx4 v247, v[146:149], s[38:39]
	s_add_u32 s38, s38, 0x4000
	s_addc_u32 s39, s39, 0
	s_waitcnt vmcnt(31) lgkmcnt(1)
	v_pk_add_f32 v[150:151], v[238:239], v[150:151]
	v_pk_add_f32 v[152:153], v[240:241], v[152:153]
	ds_read_b128 v[238:241], v237 offset:7168
	global_store_dwordx4 v247, v[150:153], s[38:39]
	s_add_u32 s38, s38, 0x4000
	s_addc_u32 s39, s39, 0
	s_waitcnt vmcnt(31) lgkmcnt(1)
	v_pk_add_f32 v[154:155], v[228:229], v[154:155]
	v_pk_add_f32 v[156:157], v[230:231], v[156:157]
	ds_read_b128 v[228:231], v210 offset:8192
	global_store_dwordx4 v247, v[154:157], s[38:39]
	s_add_u32 s38, s38, 0x4000
	s_addc_u32 s39, s39, 0
	s_waitcnt vmcnt(31) lgkmcnt(1)
	v_pk_add_f32 v[158:159], v[238:239], v[158:159]
	v_pk_add_f32 v[160:161], v[240:241], v[160:161]
	ds_read_b128 v[238:241], v211 offset:9216
	global_store_dwordx4 v247, v[158:161], s[38:39]
	s_add_u32 s38, s38, 0x4000
	s_addc_u32 s39, s39, 0
	s_waitcnt vmcnt(31) lgkmcnt(1)
	v_pk_add_f32 v[162:163], v[228:229], v[162:163]
	v_pk_add_f32 v[164:165], v[230:231], v[164:165]
	ds_read_b128 v[228:231], v215 offset:10240
	global_store_dwordx4 v247, v[162:165], s[38:39]
	s_add_u32 s38, s38, 0x4000
	s_addc_u32 s39, s39, 0
	s_waitcnt vmcnt(31) lgkmcnt(1)
	v_pk_add_f32 v[166:167], v[238:239], v[166:167]
	v_pk_add_f32 v[168:169], v[240:241], v[168:169]
	ds_read_b128 v[238:241], v237 offset:11264
	global_store_dwordx4 v247, v[166:169], s[38:39]
	s_add_u32 s38, s38, 0x4000
	s_addc_u32 s39, s39, 0
	s_waitcnt vmcnt(31) lgkmcnt(1)
	v_pk_add_f32 v[192:193], v[228:229], v[192:193]
	v_pk_add_f32 v[194:195], v[230:231], v[194:195]
	ds_read_b128 v[228:231], v210 offset:12288
	global_store_dwordx4 v247, v[192:195], s[38:39]
	s_add_u32 s38, s38, 0x4000
	s_addc_u32 s39, s39, 0
	s_waitcnt vmcnt(31) lgkmcnt(1)
	v_pk_add_f32 v[196:197], v[238:239], v[196:197]
	v_pk_add_f32 v[198:199], v[240:241], v[198:199]
	ds_read_b128 v[238:241], v211 offset:13312
	global_store_dwordx4 v247, v[196:199], s[38:39]
	s_add_u32 s38, s38, 0x4000
	s_addc_u32 s39, s39, 0
	s_waitcnt vmcnt(31) lgkmcnt(1)
	v_pk_add_f32 v[200:201], v[228:229], v[200:201]
	v_pk_add_f32 v[202:203], v[230:231], v[202:203]
	ds_read_b128 v[228:231], v215 offset:14336
	global_store_dwordx4 v247, v[200:203], s[38:39]
	s_add_u32 s38, s38, 0x4000
	s_addc_u32 s39, s39, 0
	s_waitcnt vmcnt(31) lgkmcnt(1)
	v_pk_add_f32 v[216:217], v[238:239], v[216:217]
	v_pk_add_f32 v[218:219], v[240:241], v[218:219]
	ds_read_b128 v[238:241], v237 offset:15360
	global_store_dwordx4 v247, v[216:219], s[38:39]
	s_add_u32 s38, s38, 0x4000
	s_addc_u32 s39, s39, 0
	s_waitcnt vmcnt(31) lgkmcnt(1)
	v_pk_add_f32 v[220:221], v[228:229], v[220:221]
	v_pk_add_f32 v[222:223], v[230:231], v[222:223]
	global_store_dwordx4 v247, v[220:223], s[38:39]
	s_add_u32 s38, s38, 0x4000
	s_addc_u32 s39, s39, 0
	s_waitcnt vmcnt(31) lgkmcnt(0)
	v_pk_add_f32 v[224:225], v[238:239], v[224:225]
	v_pk_add_f32 v[226:227], v[240:241], v[226:227]
	global_store_dwordx4 v247, v[224:227], s[38:39]
	s_add_u32 s38, s38, 0x4000
	s_addc_u32 s39, s39, 0
	s_add_u32 s34, s34, 0x1000
	s_addc_u32 s35, s35, 0
	v_and_b32_e32 v238, 15, v170
	v_xor_b32_e32 v238, v238, v171
	v_lshl_add_u32 v239, v170, 8, s40
	v_xor_b32_e32 v228, 0, v238
	v_lshl_add_u32 v228, v228, 4, v239
	v_xor_b32_e32 v229, 2, v238
	v_lshl_add_u32 v229, v229, 4, v239
	v_xor_b32_e32 v230, 4, v238
	v_lshl_add_u32 v230, v230, 4, v239
	v_xor_b32_e32 v231, 6, v238
	v_lshl_add_u32 v231, v231, 4, v239
	v_xor_b32_e32 v232, 8, v238
	v_lshl_add_u32 v232, v232, 4, v239
	v_xor_b32_e32 v233, 10, v238
	v_lshl_add_u32 v233, v233, 4, v239
	v_xor_b32_e32 v234, 12, v238
	v_lshl_add_u32 v234, v234, 4, v239
	v_xor_b32_e32 v235, 14, v238
	v_lshl_add_u32 v235, v235, 4, v239
	ds_write_b128 v228, v[18:21]
	ds_write_b128 v229, v[22:25]
	ds_write_b128 v230, v[26:29]
	ds_write_b128 v231, v[30:33]
	ds_write_b128 v232, v[50:53]
	ds_write_b128 v233, v[54:57]
	ds_write_b128 v234, v[58:61]
	ds_write_b128 v235, v[62:65]
	ds_write_b128 v228, v[2:5] offset:8192
	ds_write_b128 v229, v[6:9] offset:8192
	ds_write_b128 v230, v[10:13] offset:8192
	ds_write_b128 v231, v[14:17] offset:8192
	ds_write_b128 v232, v[34:37] offset:8192
	ds_write_b128 v233, v[38:41] offset:8192
	ds_write_b128 v234, v[42:45] offset:8192
	ds_write_b128 v235, v[46:49] offset:8192
	s_waitcnt lgkmcnt(0)
	ds_read_b128 v[228:231], v210 offset:0
	ds_read_b128 v[238:241], v211 offset:1024
	s_waitcnt vmcnt(31) lgkmcnt(1)
	v_pk_add_f32 v[66:67], v[228:229], v[66:67]
	v_pk_add_f32 v[68:69], v[230:231], v[68:69]
	ds_read_b128 v[228:231], v215 offset:2048
	global_store_dwordx4 v247, v[66:69], s[38:39]
	s_add_u32 s38, s38, 0x4000
	s_addc_u32 s39, s39, 0
	s_waitcnt vmcnt(31) lgkmcnt(1)
	v_pk_add_f32 v[70:71], v[238:239], v[70:71]
	v_pk_add_f32 v[72:73], v[240:241], v[72:73]
	ds_read_b128 v[238:241], v237 offset:3072
	global_store_dwordx4 v247, v[70:73], s[38:39]
	s_add_u32 s38, s38, 0x4000
	s_addc_u32 s39, s39, 0
	s_waitcnt vmcnt(31) lgkmcnt(1)
	v_pk_add_f32 v[74:75], v[228:229], v[74:75]
	v_pk_add_f32 v[76:77], v[230:231], v[76:77]
	ds_read_b128 v[228:231], v210 offset:4096
	global_store_dwordx4 v247, v[74:77], s[38:39]
	s_add_u32 s38, s38, 0x4000
	s_addc_u32 s39, s39, 0
	s_waitcnt vmcnt(31) lgkmcnt(1)
	v_pk_add_f32 v[78:79], v[238:239], v[78:79]
	v_pk_add_f32 v[80:81], v[240:241], v[80:81]
	ds_read_b128 v[238:241], v211 offset:5120
	global_store_dwordx4 v247, v[78:81], s[38:39]
	s_add_u32 s38, s38, 0x4000
	s_addc_u32 s39, s39, 0
	s_waitcnt vmcnt(31) lgkmcnt(1)
	v_pk_add_f32 v[114:115], v[228:229], v[114:115]
	v_pk_add_f32 v[116:117], v[230:231], v[116:117]
	ds_read_b128 v[228:231], v215 offset:6144
	global_store_dwordx4 v247, v[114:117], s[38:39]
	s_add_u32 s38, s38, 0x4000
	s_addc_u32 s39, s39, 0
	s_waitcnt vmcnt(31) lgkmcnt(1)
	v_pk_add_f32 v[118:119], v[238:239], v[118:119]
	v_pk_add_f32 v[120:121], v[240:241], v[120:121]
	ds_read_b128 v[238:241], v237 offset:7168
	global_store_dwordx4 v247, v[118:121], s[38:39]
	s_add_u32 s38, s38, 0x4000
	s_addc_u32 s39, s39, 0
	s_waitcnt vmcnt(31) lgkmcnt(1)
	v_pk_add_f32 v[122:123], v[228:229], v[122:123]
	v_pk_add_f32 v[124:125], v[230:231], v[124:125]
	ds_read_b128 v[228:231], v210 offset:8192
	global_store_dwordx4 v247, v[122:125], s[38:39]
	s_add_u32 s38, s38, 0x4000
	s_addc_u32 s39, s39, 0
	s_waitcnt vmcnt(31) lgkmcnt(1)
	v_pk_add_f32 v[126:127], v[238:239], v[126:127]
	v_pk_add_f32 v[128:129], v[240:241], v[128:129]
	ds_read_b128 v[238:241], v211 offset:9216
	global_store_dwordx4 v247, v[126:129], s[38:39]
	s_add_u32 s38, s38, 0x4000
	s_addc_u32 s39, s39, 0
	s_waitcnt vmcnt(31) lgkmcnt(1)
	v_pk_add_f32 v[82:83], v[228:229], v[82:83]
	v_pk_add_f32 v[84:85], v[230:231], v[84:85]
	ds_read_b128 v[228:231], v215 offset:10240
	global_store_dwordx4 v247, v[82:85], s[38:39]
	s_add_u32 s38, s38, 0x4000
	s_addc_u32 s39, s39, 0
	s_waitcnt vmcnt(31) lgkmcnt(1)
	v_pk_add_f32 v[86:87], v[238:239], v[86:87]
	v_pk_add_f32 v[88:89], v[240:241], v[88:89]
	ds_read_b128 v[238:241], v237 offset:11264
	global_store_dwordx4 v247, v[86:89], s[38:39]
	s_add_u32 s38, s38, 0x4000
	s_addc_u32 s39, s39, 0
	s_waitcnt vmcnt(31) lgkmcnt(1)
	v_pk_add_f32 v[90:91], v[228:229], v[90:91]
	v_pk_add_f32 v[92:93], v[230:231], v[92:93]
	ds_read_b128 v[228:231], v210 offset:12288
	global_store_dwordx4 v247, v[90:93], s[38:39]
	s_add_u32 s38, s38, 0x4000
	s_addc_u32 s39, s39, 0
	s_waitcnt vmcnt(31) lgkmcnt(1)
	v_pk_add_f32 v[94:95], v[238:239], v[94:95]
	v_pk_add_f32 v[96:97], v[240:241], v[96:97]
	ds_read_b128 v[238:241], v211 offset:13312
	global_store_dwordx4 v247, v[94:97], s[38:39]
	s_add_u32 s38, s38, 0x4000
	s_addc_u32 s39, s39, 0
	s_waitcnt vmcnt(31) lgkmcnt(1)
	v_pk_add_f32 v[98:99], v[228:229], v[98:99]
	v_pk_add_f32 v[100:101], v[230:231], v[100:101]
	ds_read_b128 v[228:231], v215 offset:14336
	global_store_dwordx4 v247, v[98:101], s[38:39]
	s_add_u32 s38, s38, 0x4000
	s_addc_u32 s39, s39, 0
	s_waitcnt vmcnt(31) lgkmcnt(1)
	v_pk_add_f32 v[102:103], v[238:239], v[102:103]
	v_pk_add_f32 v[104:105], v[240:241], v[104:105]
	ds_read_b128 v[238:241], v237 offset:15360
	global_store_dwordx4 v247, v[102:105], s[38:39]
	s_add_u32 s38, s38, 0x4000
	s_addc_u32 s39, s39, 0
	s_waitcnt vmcnt(31) lgkmcnt(1)
	v_pk_add_f32 v[106:107], v[228:229], v[106:107]
	v_pk_add_f32 v[108:109], v[230:231], v[108:109]
	global_store_dwordx4 v247, v[106:109], s[38:39]
	s_add_u32 s38, s38, 0x4000
	s_addc_u32 s39, s39, 0
	s_waitcnt vmcnt(31) lgkmcnt(0)
	v_pk_add_f32 v[110:111], v[238:239], v[110:111]
	v_pk_add_f32 v[112:113], v[240:241], v[112:113]
	global_store_dwordx4 v247, v[110:113], s[38:39]
	s_add_u32 s38, s38, 0x4000
	s_addc_u32 s39, s39, 0
	s_waitcnt lgkmcnt(0)
	s_branch .LBB0_1677
